# epilogues-16wide+ssq-lds-cache-in-Sa
# speedup vs baseline: 1.0858x; 1.0059x over previous
.LBB0_209:
	s_or_b64 exec, exec, s[48:49]
	v_lshlrev_b32_e32 v0, 10, v129
	v_and_b32_e32 v0, 0x3000, v0
	v_add_u32_e32 v34, v120, v0
	v_ashrrev_i32_e32 v35, 31, v34
	v_lshlrev_b64 v[34:35], 11, v[34:35]
	v_lshlrev_b32_e32 v0, 7, v129
	v_lshl_add_u64 v[34:35], s[70:71], 0, v[34:35]
	v_and_b32_e32 v0, 0x180, v0
	v_lshl_add_u64 v[34:35], v[34:35], 0, v[0:1]
	v_lshlrev_b32_e32 v0, 3, v115
	v_lshl_add_u64 v[36:37], v[34:35], 0, v[0:1]
	s_mov_b64 s[38:39], 0x95c8600
	v_lshl_add_u64 v[34:35], v[36:37], 0, s[38:39]
	v_add_co_u32_e32 v36, vcc, 0x95c8000, v36
	s_nop 1
	v_addc_co_u32_e32 v37, vcc, 0, v37, vcc
	global_load_dwordx2 v[44:45], v[34:35], off
	global_load_dwordx2 v[46:47], v[34:35], off offset:16
	global_load_dwordx2 v[48:49], v[34:35], off offset:32
	global_load_dwordx2 v[50:51], v[34:35], off offset:48
	global_load_dwordx2 v[52:53], v[34:35], off offset:64
	global_load_dwordx2 v[54:55], v[34:35], off offset:80
	global_load_dwordx2 v[56:57], v[34:35], off offset:96
	global_load_dwordx2 v[58:59], v[34:35], off offset:112
	s_mov_b32 s38, 0xbfb8aa3b
	s_mov_b32 s39, 0xbfb8aa3b
	s_mov_b32 s48, 1.0
	s_mov_b32 s49, 1.0
	s_waitcnt vmcnt(0)
	v_lshlrev_b32_e32 v64, 16, v44
	v_and_b32_e32 v65, 0xffff0000, v44
	v_lshlrev_b32_e32 v66, 16, v45
	v_and_b32_e32 v67, 0xffff0000, v45
	v_lshlrev_b32_e32 v68, 16, v46
	v_and_b32_e32 v69, 0xffff0000, v46
	v_lshlrev_b32_e32 v70, 16, v47
	v_and_b32_e32 v71, 0xffff0000, v47
	v_lshlrev_b32_e32 v72, 16, v48
	v_and_b32_e32 v73, 0xffff0000, v48
	v_lshlrev_b32_e32 v74, 16, v49
	v_and_b32_e32 v75, 0xffff0000, v49
	v_lshlrev_b32_e32 v76, 16, v50
	v_and_b32_e32 v77, 0xffff0000, v50
	v_lshlrev_b32_e32 v78, 16, v51
	v_and_b32_e32 v79, 0xffff0000, v51
	v_pk_mul_f32 v[80:81], v[64:65], s[38:39]
	v_pk_mul_f32 v[82:83], v[66:67], s[38:39]
	v_pk_mul_f32 v[84:85], v[68:69], s[38:39]
	v_pk_mul_f32 v[86:87], v[70:71], s[38:39]
	v_pk_mul_f32 v[88:89], v[72:73], s[38:39]
	v_pk_mul_f32 v[90:91], v[74:75], s[38:39]
	v_pk_mul_f32 v[92:93], v[76:77], s[38:39]
	v_pk_mul_f32 v[94:95], v[78:79], s[38:39]
	v_exp_f32_e32 v80, v80
	v_exp_f32_e32 v81, v81
	v_exp_f32_e32 v82, v82
	v_exp_f32_e32 v83, v83
	v_exp_f32_e32 v84, v84
	v_exp_f32_e32 v85, v85
	v_exp_f32_e32 v86, v86
	v_exp_f32_e32 v87, v87
	v_exp_f32_e32 v88, v88
	v_exp_f32_e32 v89, v89
	v_exp_f32_e32 v90, v90
	v_exp_f32_e32 v91, v91
	v_exp_f32_e32 v92, v92
	v_exp_f32_e32 v93, v93
	v_exp_f32_e32 v94, v94
	v_exp_f32_e32 v95, v95
	v_pk_add_f32 v[80:81], v[80:81], s[48:49]
	v_pk_add_f32 v[82:83], v[82:83], s[48:49]
	v_pk_add_f32 v[84:85], v[84:85], s[48:49]
	v_pk_add_f32 v[86:87], v[86:87], s[48:49]
	v_pk_add_f32 v[88:89], v[88:89], s[48:49]
	v_pk_add_f32 v[90:91], v[90:91], s[48:49]
	v_pk_add_f32 v[92:93], v[92:93], s[48:49]
	v_pk_add_f32 v[94:95], v[94:95], s[48:49]
	v_rcp_f32_e32 v80, v80
	v_rcp_f32_e32 v81, v81
	v_rcp_f32_e32 v82, v82
	v_rcp_f32_e32 v83, v83
	v_rcp_f32_e32 v84, v84
	v_rcp_f32_e32 v85, v85
	v_rcp_f32_e32 v86, v86
	v_rcp_f32_e32 v87, v87
	v_rcp_f32_e32 v88, v88
	v_rcp_f32_e32 v89, v89
	v_rcp_f32_e32 v90, v90
	v_rcp_f32_e32 v91, v91
	v_rcp_f32_e32 v92, v92
	v_rcp_f32_e32 v93, v93
	v_rcp_f32_e32 v94, v94
	v_rcp_f32_e32 v95, v95
	v_pk_mul_f32 v[80:81], v[80:81], v[64:65]
	v_pk_mul_f32 v[82:83], v[82:83], v[66:67]
	v_pk_mul_f32 v[84:85], v[84:85], v[68:69]
	v_pk_mul_f32 v[86:87], v[86:87], v[70:71]
	v_pk_mul_f32 v[88:89], v[88:89], v[72:73]
	v_pk_mul_f32 v[90:91], v[90:91], v[74:75]
	v_pk_mul_f32 v[92:93], v[92:93], v[76:77]
	v_pk_mul_f32 v[94:95], v[94:95], v[78:79]
	v_pk_mul_f32 v[80:81], v[2:3], v[80:81]
	v_pk_mul_f32 v[82:83], v[4:5], v[82:83]
	v_pk_mul_f32 v[84:85], v[6:7], v[84:85]
	v_pk_mul_f32 v[86:87], v[8:9], v[86:87]
	v_pk_mul_f32 v[88:89], v[10:11], v[88:89]
	v_pk_mul_f32 v[90:91], v[12:13], v[90:91]
	v_pk_mul_f32 v[92:93], v[14:15], v[92:93]
	v_pk_mul_f32 v[94:95], v[16:17], v[94:95]
	v_cvt_pk_bf16_f32 v64, v80, v81
	v_cvt_pk_bf16_f32 v65, v82, v83
	v_cvt_pk_bf16_f32 v66, v84, v85
	v_cvt_pk_bf16_f32 v67, v86, v87
	v_cvt_pk_bf16_f32 v68, v88, v89
	v_cvt_pk_bf16_f32 v69, v90, v91
	v_cvt_pk_bf16_f32 v70, v92, v93
	v_cvt_pk_bf16_f32 v71, v94, v95
	global_store_dwordx2 v[34:35], v[64:65], off
	global_store_dwordx2 v[34:35], v[66:67], off offset:16
	global_store_dwordx2 v[34:35], v[68:69], off offset:32
	global_store_dwordx2 v[34:35], v[70:71], off offset:48
	v_lshlrev_b32_e32 v64, 16, v52
	v_and_b32_e32 v65, 0xffff0000, v52
	v_lshlrev_b32_e32 v66, 16, v53
	v_and_b32_e32 v67, 0xffff0000, v53
	v_lshlrev_b32_e32 v68, 16, v54
	v_and_b32_e32 v69, 0xffff0000, v54
	v_lshlrev_b32_e32 v70, 16, v55
	v_and_b32_e32 v71, 0xffff0000, v55
	v_lshlrev_b32_e32 v72, 16, v56
	v_and_b32_e32 v73, 0xffff0000, v56
	v_lshlrev_b32_e32 v74, 16, v57
	v_and_b32_e32 v75, 0xffff0000, v57
	v_lshlrev_b32_e32 v76, 16, v58
	v_and_b32_e32 v77, 0xffff0000, v58
	v_lshlrev_b32_e32 v78, 16, v59
	v_and_b32_e32 v79, 0xffff0000, v59
	v_pk_mul_f32 v[80:81], v[64:65], s[38:39]
	v_pk_mul_f32 v[82:83], v[66:67], s[38:39]
	v_pk_mul_f32 v[84:85], v[68:69], s[38:39]
	v_pk_mul_f32 v[86:87], v[70:71], s[38:39]
	v_pk_mul_f32 v[88:89], v[72:73], s[38:39]
	v_pk_mul_f32 v[90:91], v[74:75], s[38:39]
	v_pk_mul_f32 v[92:93], v[76:77], s[38:39]
	v_pk_mul_f32 v[94:95], v[78:79], s[38:39]
	v_exp_f32_e32 v80, v80
	v_exp_f32_e32 v81, v81
	v_exp_f32_e32 v82, v82
	v_exp_f32_e32 v83, v83
	v_exp_f32_e32 v84, v84
	v_exp_f32_e32 v85, v85
	v_exp_f32_e32 v86, v86
	v_exp_f32_e32 v87, v87
	v_exp_f32_e32 v88, v88
	v_exp_f32_e32 v89, v89
	v_exp_f32_e32 v90, v90
	v_exp_f32_e32 v91, v91
	v_exp_f32_e32 v92, v92
	v_exp_f32_e32 v93, v93
	v_exp_f32_e32 v94, v94
	v_exp_f32_e32 v95, v95
	v_pk_add_f32 v[80:81], v[80:81], s[48:49]
	v_pk_add_f32 v[82:83], v[82:83], s[48:49]
	v_pk_add_f32 v[84:85], v[84:85], s[48:49]
	v_pk_add_f32 v[86:87], v[86:87], s[48:49]
	v_pk_add_f32 v[88:89], v[88:89], s[48:49]
	v_pk_add_f32 v[90:91], v[90:91], s[48:49]
	v_pk_add_f32 v[92:93], v[92:93], s[48:49]
	v_pk_add_f32 v[94:95], v[94:95], s[48:49]
	v_rcp_f32_e32 v80, v80
	v_rcp_f32_e32 v81, v81
	v_rcp_f32_e32 v82, v82
	v_rcp_f32_e32 v83, v83
	v_rcp_f32_e32 v84, v84
	v_rcp_f32_e32 v85, v85
	v_rcp_f32_e32 v86, v86
	v_rcp_f32_e32 v87, v87
	v_rcp_f32_e32 v88, v88
	v_rcp_f32_e32 v89, v89
	v_rcp_f32_e32 v90, v90
	v_rcp_f32_e32 v91, v91
	v_rcp_f32_e32 v92, v92
	v_rcp_f32_e32 v93, v93
	v_rcp_f32_e32 v94, v94
	v_rcp_f32_e32 v95, v95
	v_pk_mul_f32 v[80:81], v[80:81], v[64:65]
	v_pk_mul_f32 v[82:83], v[82:83], v[66:67]
	v_pk_mul_f32 v[84:85], v[84:85], v[68:69]
	v_pk_mul_f32 v[86:87], v[86:87], v[70:71]
	v_pk_mul_f32 v[88:89], v[88:89], v[72:73]
	v_pk_mul_f32 v[90:91], v[90:91], v[74:75]
	v_pk_mul_f32 v[92:93], v[92:93], v[76:77]
	v_pk_mul_f32 v[94:95], v[94:95], v[78:79]
	v_pk_mul_f32 v[80:81], v[18:19], v[80:81]
	v_pk_mul_f32 v[82:83], v[20:21], v[82:83]
	v_pk_mul_f32 v[84:85], v[22:23], v[84:85]
	v_pk_mul_f32 v[86:87], v[24:25], v[86:87]
	v_pk_mul_f32 v[88:89], v[26:27], v[88:89]
	v_pk_mul_f32 v[90:91], v[28:29], v[90:91]
	v_pk_mul_f32 v[92:93], v[30:31], v[92:93]
	v_pk_mul_f32 v[94:95], v[32:33], v[94:95]
	v_cvt_pk_bf16_f32 v64, v80, v81
	v_cvt_pk_bf16_f32 v65, v82, v83
	v_cvt_pk_bf16_f32 v66, v84, v85
	v_cvt_pk_bf16_f32 v67, v86, v87
	v_cvt_pk_bf16_f32 v68, v88, v89
	v_cvt_pk_bf16_f32 v69, v90, v91
	v_cvt_pk_bf16_f32 v70, v92, v93
	v_cvt_pk_bf16_f32 v71, v94, v95
	global_store_dwordx2 v[34:35], v[64:65], off offset:64
	global_store_dwordx2 v[34:35], v[66:67], off offset:80
	global_store_dwordx2 v[34:35], v[68:69], off offset:96
	global_store_dwordx2 v[34:35], v[70:71], off offset:112
	s_waitcnt lgkmcnt(0)
	s_barrier

.LBB0_257:
	s_or_b64 exec, exec, s[42:43]
	v_xor_b32_e32 v0, 32, v216
	v_add_u32_e32 v2, 64, v113
	v_cmp_lt_i32_e32 vcc, v0, v2
	v_readlane_b32 s38, v251, 27
	v_readlane_b32 s39, v251, 28
	v_cndmask_b32_e32 v0, v216, v0, vcc
	v_lshlrev_b32_e32 v0, 2, v0
	ds_bpermute_b32 v0, v0, v148
	s_waitcnt lgkmcnt(0)
	v_add_f32_e32 v0, v148, v0
	v_rcp_f32_e32 v4, v0
	v_lshlrev_b32_e32 v0, 9, v120
	v_and_b32_e32 v0, 0x3000, v0
	v_add_u32_e32 v2, v112, v0
	v_ashrrev_i32_e32 v3, 31, v2
	v_lshlrev_b64 v[2:3], 11, v[2:3]
	v_lshlrev_b32_e32 v0, 7, v120
	v_lshl_add_u64 v[2:3], s[38:39], 0, v[2:3]
	v_and_b32_e32 v0, 0x380, v0
	v_lshl_add_u64 v[2:3], v[2:3], 0, v[0:1]
	v_lshlrev_b32_e32 v0, 3, v121
	v_lshl_add_u64 v[2:3], v[2:3], 0, v[0:1]
	global_load_dwordx2 v[192:193], v[2:3], off
	global_load_dwordx2 v[194:195], v[2:3], off offset:16
	global_load_dwordx2 v[196:197], v[2:3], off offset:32
	global_load_dwordx2 v[198:199], v[2:3], off offset:48
	global_load_dwordx2 v[200:201], v[2:3], off offset:64
	global_load_dwordx2 v[202:203], v[2:3], off offset:80
	global_load_dwordx2 v[204:205], v[2:3], off offset:96
	global_load_dwordx2 v[206:207], v[2:3], off offset:112
	s_mov_b32 s44, 0xbfb8aa3b
	s_mov_b32 s45, 0xbfb8aa3b
	s_mov_b32 s46, 1.0
	s_mov_b32 s47, 1.0
	v_pk_mul_f32 v[32:33], v[32:33], v[4:5] op_sel_hi:[1,0]
	v_pk_mul_f32 v[34:35], v[34:35], v[4:5] op_sel_hi:[1,0]
	v_pk_mul_f32 v[36:37], v[36:37], v[4:5] op_sel_hi:[1,0]
	v_pk_mul_f32 v[38:39], v[38:39], v[4:5] op_sel_hi:[1,0]
	v_pk_mul_f32 v[40:41], v[40:41], v[4:5] op_sel_hi:[1,0]
	v_pk_mul_f32 v[42:43], v[42:43], v[4:5] op_sel_hi:[1,0]
	v_pk_mul_f32 v[44:45], v[44:45], v[4:5] op_sel_hi:[1,0]
	v_pk_mul_f32 v[46:47], v[46:47], v[4:5] op_sel_hi:[1,0]
	v_pk_mul_f32 v[16:17], v[16:17], v[4:5] op_sel_hi:[1,0]
	v_pk_mul_f32 v[18:19], v[18:19], v[4:5] op_sel_hi:[1,0]
	v_pk_mul_f32 v[20:21], v[20:21], v[4:5] op_sel_hi:[1,0]
	v_pk_mul_f32 v[22:23], v[22:23], v[4:5] op_sel_hi:[1,0]
	v_pk_mul_f32 v[24:25], v[24:25], v[4:5] op_sel_hi:[1,0]
	v_pk_mul_f32 v[26:27], v[26:27], v[4:5] op_sel_hi:[1,0]
	v_pk_mul_f32 v[28:29], v[28:29], v[4:5] op_sel_hi:[1,0]
	v_pk_mul_f32 v[30:31], v[30:31], v[4:5] op_sel_hi:[1,0]
	s_waitcnt vmcnt(0)
	v_lshlrev_b32_e32 v64, 16, v192
	v_and_b32_e32 v65, 0xffff0000, v192
	v_lshlrev_b32_e32 v66, 16, v193
	v_and_b32_e32 v67, 0xffff0000, v193
	v_lshlrev_b32_e32 v68, 16, v194
	v_and_b32_e32 v69, 0xffff0000, v194
	v_lshlrev_b32_e32 v70, 16, v195
	v_and_b32_e32 v71, 0xffff0000, v195
	v_lshlrev_b32_e32 v72, 16, v196
	v_and_b32_e32 v73, 0xffff0000, v196
	v_lshlrev_b32_e32 v74, 16, v197
	v_and_b32_e32 v75, 0xffff0000, v197
	v_lshlrev_b32_e32 v76, 16, v198
	v_and_b32_e32 v77, 0xffff0000, v198
	v_lshlrev_b32_e32 v78, 16, v199
	v_and_b32_e32 v79, 0xffff0000, v199
	v_pk_mul_f32 v[80:81], v[64:65], s[44:45]
	v_pk_mul_f32 v[82:83], v[66:67], s[44:45]
	v_pk_mul_f32 v[84:85], v[68:69], s[44:45]
	v_pk_mul_f32 v[86:87], v[70:71], s[44:45]
	v_pk_mul_f32 v[88:89], v[72:73], s[44:45]
	v_pk_mul_f32 v[90:91], v[74:75], s[44:45]
	v_pk_mul_f32 v[92:93], v[76:77], s[44:45]
	v_pk_mul_f32 v[94:95], v[78:79], s[44:45]
	v_exp_f32_e32 v80, v80
	v_exp_f32_e32 v81, v81
	v_exp_f32_e32 v82, v82
	v_exp_f32_e32 v83, v83
	v_exp_f32_e32 v84, v84
	v_exp_f32_e32 v85, v85
	v_exp_f32_e32 v86, v86
	v_exp_f32_e32 v87, v87
	v_exp_f32_e32 v88, v88
	v_exp_f32_e32 v89, v89
	v_exp_f32_e32 v90, v90
	v_exp_f32_e32 v91, v91
	v_exp_f32_e32 v92, v92
	v_exp_f32_e32 v93, v93
	v_exp_f32_e32 v94, v94
	v_exp_f32_e32 v95, v95
	v_pk_add_f32 v[80:81], v[80:81], s[46:47]
	v_pk_add_f32 v[82:83], v[82:83], s[46:47]
	v_pk_add_f32 v[84:85], v[84:85], s[46:47]
	v_pk_add_f32 v[86:87], v[86:87], s[46:47]
	v_pk_add_f32 v[88:89], v[88:89], s[46:47]
	v_pk_add_f32 v[90:91], v[90:91], s[46:47]
	v_pk_add_f32 v[92:93], v[92:93], s[46:47]
	v_pk_add_f32 v[94:95], v[94:95], s[46:47]
	v_rcp_f32_e32 v80, v80
	v_rcp_f32_e32 v81, v81
	v_rcp_f32_e32 v82, v82
	v_rcp_f32_e32 v83, v83
	v_rcp_f32_e32 v84, v84
	v_rcp_f32_e32 v85, v85
	v_rcp_f32_e32 v86, v86
	v_rcp_f32_e32 v87, v87
	v_rcp_f32_e32 v88, v88
	v_rcp_f32_e32 v89, v89
	v_rcp_f32_e32 v90, v90
	v_rcp_f32_e32 v91, v91
	v_rcp_f32_e32 v92, v92
	v_rcp_f32_e32 v93, v93
	v_rcp_f32_e32 v94, v94
	v_rcp_f32_e32 v95, v95
	v_pk_mul_f32 v[80:81], v[80:81], v[64:65]
	v_pk_mul_f32 v[82:83], v[82:83], v[66:67]
	v_pk_mul_f32 v[84:85], v[84:85], v[68:69]
	v_pk_mul_f32 v[86:87], v[86:87], v[70:71]
	v_pk_mul_f32 v[88:89], v[88:89], v[72:73]
	v_pk_mul_f32 v[90:91], v[90:91], v[74:75]
	v_pk_mul_f32 v[92:93], v[92:93], v[76:77]
	v_pk_mul_f32 v[94:95], v[94:95], v[78:79]
	v_pk_mul_f32 v[80:81], v[32:33], v[80:81]
	v_pk_mul_f32 v[82:83], v[34:35], v[82:83]
	v_pk_mul_f32 v[84:85], v[36:37], v[84:85]
	v_pk_mul_f32 v[86:87], v[38:39], v[86:87]
	v_pk_mul_f32 v[88:89], v[40:41], v[88:89]
	v_pk_mul_f32 v[90:91], v[42:43], v[90:91]
	v_pk_mul_f32 v[92:93], v[44:45], v[92:93]
	v_pk_mul_f32 v[94:95], v[46:47], v[94:95]
	v_cvt_pk_bf16_f32 v64, v80, v81
	v_cvt_pk_bf16_f32 v65, v82, v83
	v_cvt_pk_bf16_f32 v66, v84, v85
	v_cvt_pk_bf16_f32 v67, v86, v87
	v_cvt_pk_bf16_f32 v68, v88, v89
	v_cvt_pk_bf16_f32 v69, v90, v91
	v_cvt_pk_bf16_f32 v70, v92, v93
	v_cvt_pk_bf16_f32 v71, v94, v95
	global_store_dwordx2 v[2:3], v[64:65], off
	global_store_dwordx2 v[2:3], v[66:67], off offset:16
	global_store_dwordx2 v[2:3], v[68:69], off offset:32
	global_store_dwordx2 v[2:3], v[70:71], off offset:48
	v_lshlrev_b32_e32 v64, 16, v200
	v_and_b32_e32 v65, 0xffff0000, v200
	v_lshlrev_b32_e32 v66, 16, v201
	v_and_b32_e32 v67, 0xffff0000, v201
	v_lshlrev_b32_e32 v68, 16, v202
	v_and_b32_e32 v69, 0xffff0000, v202
	v_lshlrev_b32_e32 v70, 16, v203
	v_and_b32_e32 v71, 0xffff0000, v203
	v_lshlrev_b32_e32 v72, 16, v204
	v_and_b32_e32 v73, 0xffff0000, v204
	v_lshlrev_b32_e32 v74, 16, v205
	v_and_b32_e32 v75, 0xffff0000, v205
	v_lshlrev_b32_e32 v76, 16, v206
	v_and_b32_e32 v77, 0xffff0000, v206
	v_lshlrev_b32_e32 v78, 16, v207
	v_and_b32_e32 v79, 0xffff0000, v207
	v_pk_mul_f32 v[80:81], v[64:65], s[44:45]
	v_pk_mul_f32 v[82:83], v[66:67], s[44:45]
	v_pk_mul_f32 v[84:85], v[68:69], s[44:45]
	v_pk_mul_f32 v[86:87], v[70:71], s[44:45]
	v_pk_mul_f32 v[88:89], v[72:73], s[44:45]
	v_pk_mul_f32 v[90:91], v[74:75], s[44:45]
	v_pk_mul_f32 v[92:93], v[76:77], s[44:45]
	v_pk_mul_f32 v[94:95], v[78:79], s[44:45]
	v_exp_f32_e32 v80, v80
	v_exp_f32_e32 v81, v81
	v_exp_f32_e32 v82, v82
	v_exp_f32_e32 v83, v83
	v_exp_f32_e32 v84, v84
	v_exp_f32_e32 v85, v85
	v_exp_f32_e32 v86, v86
	v_exp_f32_e32 v87, v87
	v_exp_f32_e32 v88, v88
	v_exp_f32_e32 v89, v89
	v_exp_f32_e32 v90, v90
	v_exp_f32_e32 v91, v91
	v_exp_f32_e32 v92, v92
	v_exp_f32_e32 v93, v93
	v_exp_f32_e32 v94, v94
	v_exp_f32_e32 v95, v95
	v_pk_add_f32 v[80:81], v[80:81], s[46:47]
	v_pk_add_f32 v[82:83], v[82:83], s[46:47]
	v_pk_add_f32 v[84:85], v[84:85], s[46:47]
	v_pk_add_f32 v[86:87], v[86:87], s[46:47]
	v_pk_add_f32 v[88:89], v[88:89], s[46:47]
	v_pk_add_f32 v[90:91], v[90:91], s[46:47]
	v_pk_add_f32 v[92:93], v[92:93], s[46:47]
	v_pk_add_f32 v[94:95], v[94:95], s[46:47]
	v_rcp_f32_e32 v80, v80
	v_rcp_f32_e32 v81, v81
	v_rcp_f32_e32 v82, v82
	v_rcp_f32_e32 v83, v83
	v_rcp_f32_e32 v84, v84
	v_rcp_f32_e32 v85, v85
	v_rcp_f32_e32 v86, v86
	v_rcp_f32_e32 v87, v87
	v_rcp_f32_e32 v88, v88
	v_rcp_f32_e32 v89, v89
	v_rcp_f32_e32 v90, v90
	v_rcp_f32_e32 v91, v91
	v_rcp_f32_e32 v92, v92
	v_rcp_f32_e32 v93, v93
	v_rcp_f32_e32 v94, v94
	v_rcp_f32_e32 v95, v95
	v_pk_mul_f32 v[80:81], v[80:81], v[64:65]
	v_pk_mul_f32 v[82:83], v[82:83], v[66:67]
	v_pk_mul_f32 v[84:85], v[84:85], v[68:69]
	v_pk_mul_f32 v[86:87], v[86:87], v[70:71]
	v_pk_mul_f32 v[88:89], v[88:89], v[72:73]
	v_pk_mul_f32 v[90:91], v[90:91], v[74:75]
	v_pk_mul_f32 v[92:93], v[92:93], v[76:77]
	v_pk_mul_f32 v[94:95], v[94:95], v[78:79]
	v_pk_mul_f32 v[80:81], v[16:17], v[80:81]
	v_pk_mul_f32 v[82:83], v[18:19], v[82:83]
	v_pk_mul_f32 v[84:85], v[20:21], v[84:85]
	v_pk_mul_f32 v[86:87], v[22:23], v[86:87]
	v_pk_mul_f32 v[88:89], v[24:25], v[88:89]
	v_pk_mul_f32 v[90:91], v[26:27], v[90:91]
	v_pk_mul_f32 v[92:93], v[28:29], v[92:93]
	v_pk_mul_f32 v[94:95], v[30:31], v[94:95]
	v_cvt_pk_bf16_f32 v64, v80, v81
	v_cvt_pk_bf16_f32 v65, v82, v83
	v_cvt_pk_bf16_f32 v66, v84, v85
	v_cvt_pk_bf16_f32 v67, v86, v87
	v_cvt_pk_bf16_f32 v68, v88, v89
	v_cvt_pk_bf16_f32 v69, v90, v91
	v_cvt_pk_bf16_f32 v70, v92, v93
	v_cvt_pk_bf16_f32 v71, v94, v95
	global_store_dwordx2 v[2:3], v[64:65], off offset:64
	global_store_dwordx2 v[2:3], v[66:67], off offset:80
	global_store_dwordx2 v[2:3], v[68:69], off offset:96
	global_store_dwordx2 v[2:3], v[70:71], off offset:112

.LBB0_489:
	s_mov_b32 s98, 0
	s_mul_i32 s0, s17, 0x700000
	s_mul_hi_u32 s1, s16, 0x700000
	s_add_i32 s1, s1, s0
	s_mul_i32 s0, s16, 0x700000
	s_add_u32 s47, s66, s0
	s_addc_u32 s48, s67, s1
	v_readlane_b32 s0, v252, 22
	v_mov_b32_e32 v6, v212
	v_readlane_b32 s1, v252, 23
	s_andn2_b64 vcc, exec, s[0:1]
	v_readfirstlane_b32 s4, v6
	s_cbranch_vccnz .LBB0_729
	v_lshlrev_b32_e32 v2, 4, v6
	v_add_u32_e32 v3, 0x2000, v2
	v_ashrrev_i32_e32 v0, 31, v3
	v_lshrrev_b32_e32 v0, 22, v0
	v_add_u32_e32 v0, v3, v0
	v_ashrrev_i32_e32 v0, 10, v0
	v_mul_i32_i24_e32 v4, 0x400, v0
	v_sub_u32_e32 v3, v3, v4
	v_lshrrev_b32_e32 v4, 4, v3
	v_bitop3_b32 v3, v4, v3, 32 bitop3:0x6c
	v_ashrrev_i32_e32 v4, 31, v3
	v_lshrrev_b32_e32 v4, 26, v4
	v_add_u32_e32 v4, v3, v4
	v_lshlrev_b32_e32 v5, 3, v0
	v_ashrrev_i32_e32 v7, 6, v4
	v_and_b32_e32 v5, -16, v5
	v_add_u32_e32 v5, v7, v5
	v_and_b32_e32 v8, 3, v7
	s_mov_b32 s0, 0x1fffe0
	v_lshrrev_b32_e32 v9, 2, v5
	v_lshlrev_b32_e32 v10, 1, v5
	v_and_b32_e32 v4, 0xc0, v4
	v_and_or_b32 v8, v5, s0, v8
	v_and_b32_e32 v9, 4, v9
	v_and_b32_e32 v10, 24, v10
	v_sub_u32_e32 v3, v3, v4
	v_or3_b32 v9, v8, v9, v10
	v_lshlrev_b32_e32 v8, 5, v0
	v_ashrrev_i16_sdwa v3, v217, sext(v3) dst_sel:DWORD dst_unused:UNUSED_PAD src0_sel:DWORD src1_sel:BYTE_0
	v_and_b32_e32 v10, 32, v8
	v_bfe_i32 v8, v3, 0, 16
	v_add_lshl_u32 v3, v10, v8, 1
	v_lshl_add_u32 v130, v9, 11, v3
	v_lshl_add_u32 v132, v5, 11, v3
	v_bfe_i32 v3, v6, 27, 1
	v_lshrrev_b32_e32 v3, 22, v3
	v_add_u32_e32 v3, v2, v3
	v_and_b32_e32 v3, 0xfffffc00, v3
	v_sub_u32_e32 v2, v2, v3
	v_lshrrev_b32_e32 v3, 4, v2
	v_ashrrev_i32_e32 v4, 31, v6
	v_bitop3_b32 v2, v3, v2, 32 bitop3:0x6c
	v_lshrrev_b32_e32 v4, 26, v4
	v_ashrrev_i32_e32 v3, 31, v2
	v_add_u32_e32 v4, v6, v4
	v_lshrrev_b32_e32 v3, 26, v3
	v_ashrrev_i32_e32 v10, 6, v4
	v_add_u32_e32 v3, v2, v3
	v_lshlrev_b32_e32 v4, 3, v10
	v_ashrrev_i32_e32 v9, 6, v3
	v_and_b32_e32 v4, -16, v4
	v_add_u32_e32 v4, v9, v4
	v_and_b32_e32 v5, 3, v9
	v_lshrrev_b32_e32 v11, 2, v4
	v_lshlrev_b32_e32 v12, 1, v4
	v_and_b32_e32 v3, 0xc0, v3
	s_ashr_i32 s6, s4, 6
	v_and_or_b32 v5, v4, s0, v5
	v_and_b32_e32 v11, 4, v11
	v_and_b32_e32 v12, 24, v12
	v_sub_u32_e32 v2, v2, v3
	s_ashr_i32 s5, s4, 8
	s_lshl_b32 s49, s6, 10
	v_or3_b32 v5, v5, v11, v12
	v_lshlrev_b32_e32 v11, 5, v10
	v_ashrrev_i16_sdwa v2, v217, sext(v2) dst_sel:DWORD dst_unused:UNUSED_PAD src0_sel:DWORD src1_sel:BYTE_0
	v_readlane_b32 s0, v251, 8
	v_and_b32_e32 v12, 32, v11
	v_bfe_i32 v11, v2, 0, 16
	v_readlane_b32 s1, v251, 9
	s_add_u32 s20, s47, s0
	v_add_lshl_u32 v2, v12, v11, 1
	s_addc_u32 s21, s48, s1
	s_add_i32 s50, s49, 0
	v_lshl_add_u32 v134, v5, 11, v2
	s_add_i32 m0, s50, 0x10000
	v_lshl_add_u32 v136, v4, 11, v2
	global_load_lds_dwordx4 v134, s[20:21]
	s_add_i32 m0, s50, 0x12000
	s_add_u32 s0, s20, 0x40000
	global_load_lds_dwordx4 v130, s[20:21]
	s_addc_u32 s1, s21, 0
	s_add_i32 m0, s50, 0x14000
	s_add_i32 s51, s50, 0x2000
	global_load_lds_dwordx4 v134, s[0:1]
	s_add_i32 m0, s50, 0x16000
	s_add_i32 s52, s50, 0x4000
	global_load_lds_dwordx4 v130, s[0:1]
	v_readlane_b32 s0, v251, 10
	s_mov_b32 m0, s50
	v_readlane_b32 s1, v251, 11
	s_add_i32 s53, s50, 0x6000
	v_mov_b32_e32 v135, v1
	v_mov_b32_e32 v131, v1
	s_cmp_eq_u32 s5, 1
	v_lshl_add_u64 v[2:3], s[20:21], 0, v[134:135]
	global_load_lds_dwordx4 v136, s[0:1]
	s_mov_b32 m0, s51
	v_lshl_add_u64 v[4:5], s[20:21], 0, v[130:131]
	global_load_lds_dwordx4 v132, s[0:1]
	v_readlane_b32 s0, v251, 12
	s_mov_b32 m0, s52
	v_readlane_b32 s1, v251, 13
	s_nop 4
	global_load_lds_dwordx4 v136, s[0:1]
	s_mov_b32 m0, s53
	s_nop 0
	global_load_lds_dwordx4 v132, s[0:1]
	s_cselect_b64 s[0:1], -1, 0
	s_cmp_lg_u32 s5, 1
	s_cbranch_scc1 .LBB0_492
	s_barrier

.LBB0_501:
	v_mov_b32_e32 v0, v164
	v_mov_b32_e32 v142, v159
	s_lshl_b32 s9, s24, 8
	s_add_i32 s9, s9, s59
	v_add_u32_e32 v160, s9, v142
	v_lshlrev_b32_e32 v142, 2, v0
	v_ashrrev_i32_e32 v143, 31, v142
	v_ashrrev_i32_e32 v161, 31, v160
	v_add_u32_e32 v156, 16, v160
	v_lshl_add_u64 v[142:143], v[142:143], 2, s[30:31]
	v_lshlrev_b64 v[144:145], 6, v[160:161]
	v_ashrrev_i32_e32 v157, 31, v156
	v_add_u32_e32 v154, 32, v160
	v_lshl_add_u64 v[162:163], v[142:143], 0, v[144:145]
	v_lshlrev_b64 v[144:145], 6, v[156:157]
	v_ashrrev_i32_e32 v155, 31, v154
	v_add_u32_e32 v152, 48, v160
	v_lshl_add_u64 v[168:169], v[142:143], 0, v[144:145]
	v_lshlrev_b64 v[144:145], 6, v[154:155]
	v_ashrrev_i32_e32 v153, 31, v152
	v_add_u32_e32 v150, 0x80, v160
	v_lshl_add_u64 v[192:193], v[142:143], 0, v[144:145]
	v_lshlrev_b64 v[144:145], 6, v[152:153]
	v_ashrrev_i32_e32 v151, 31, v150
	v_add_u32_e32 v148, 0x90, v160
	v_lshl_add_u64 v[188:189], v[142:143], 0, v[144:145]
	v_lshlrev_b64 v[144:145], 6, v[150:151]
	v_ashrrev_i32_e32 v149, 31, v148
	v_add_u32_e32 v146, 0xa0, v160
	v_lshl_add_u64 v[190:191], v[142:143], 0, v[144:145]
	v_lshlrev_b64 v[144:145], 6, v[148:149]
	v_ashrrev_i32_e32 v147, 31, v146
	v_lshl_add_u64 v[194:195], v[142:143], 0, v[144:145]
	v_lshlrev_b64 v[144:145], 6, v[146:147]
	v_lshl_add_u64 v[196:197], v[142:143], 0, v[144:145]
	v_add_u32_e32 v144, 0xb0, v160
	v_ashrrev_i32_e32 v145, 31, v144
	v_lshlrev_b64 v[184:185], 6, v[144:145]
	v_lshl_add_u64 v[142:143], v[142:143], 0, v[184:185]
	s_cmp_lg_u32 s98, 0
	s_cbranch_scc1 .Lssq_cached
	global_load_dwordx4 v[184:187], v[162:163], off
	global_load_dwordx4 v[198:201], v[142:143], off
	global_load_dwordx4 v[202:205], v[196:197], off
	global_load_dwordx4 v[206:209], v[194:195], off
	global_load_dwordx4 v[226:229], v[190:191], off
	s_nop 0
	global_load_dwordx4 v[188:191], v[188:189], off
	s_nop 0
	global_load_dwordx4 v[230:233], v[192:193], off
	s_nop 0
	global_load_dwordx4 v[192:195], v[168:169], off
	v_and_b32_e32 v143, 64, v216
	v_xor_b32_e32 v142, 16, v216
	v_add_u32_e32 v143, 64, v143
	v_cmp_lt_i32_e32 vcc, v142, v143
	s_cmp_gt_i32 s66, 3
	s_cselect_b64 s[20:21], -1, 0
	v_cndmask_b32_e32 v142, v216, v142, vcc
	v_lshlrev_b32_e32 v167, 2, v142
	v_xor_b32_e32 v142, 32, v216
	v_cmp_lt_i32_e32 vcc, v142, v143
	s_and_b32 s9, s66, 0x7ffffffe
	s_cmp_lg_u32 s9, 4
	v_cndmask_b32_e32 v142, v216, v142, vcc
	v_lshlrev_b32_e32 v168, 2, v142
	s_cselect_b64 s[18:19], -1, 0
	s_cmp_eq_u32 s66, 12
	s_cselect_b64 s[40:41], -1, 0
	s_cmp_lg_u32 s66, 12
	s_cselect_b64 s[22:23], -1, 0
	s_and_b64 s[22:23], s[22:23], s[18:19]
	s_cmp_lg_u32 s9, 6
	s_cselect_b64 s[18:19], -1, 0
	s_lshl_b32 s42, s66, 2
	s_lshl_b32 s67, s66, 8
	s_add_i32 s11, s42, s63
	s_cmp_lt_i32 s66, 2
	s_cselect_b64 s[38:39], -1, 0
	s_and_b64 s[24:25], s[38:39], exec
	s_mov_b32 s9, 0x4548000
	s_cselect_b32 s9, s9, 0x5548000
	v_and_b32_e32 v197, 0xfff, v160
	s_mov_b64 s[24:25], -1
	s_and_b64 vcc, exec, s[20:21]
	s_waitcnt vmcnt(0)
	s_nop 0
	v_add_f32_e32 v142, v184, v185
	v_add_f32_e32 v143, v186, v187
	v_add_f32_e32 v142, v142, v143
	ds_bpermute_b32 v143, v167, v142
	s_waitcnt lgkmcnt(0)
	v_add_f32_e32 v142, v142, v143
	ds_bpermute_b32 v143, v168, v142
	s_waitcnt lgkmcnt(0)
	v_add_f32_e32 v142, v142, v143
	v_mov_b32_e32 v253, v142
	v_fmamk_f32 v142, v142, 0x3a800000, v214
	v_rsq_f32_e32 v158, v142
	v_add_f32_e32 v142, v192, v193
	v_add_f32_e32 v143, v194, v195
	v_add_f32_e32 v142, v142, v143
	ds_bpermute_b32 v143, v167, v142
	s_waitcnt lgkmcnt(0)
	v_add_f32_e32 v195, v142, v143
	v_add_f32_e32 v142, v230, v231
	v_add_f32_e32 v143, v232, v233
	v_add_f32_e32 v142, v142, v143
	ds_bpermute_b32 v143, v167, v142
	ds_bpermute_b32 v196, v168, v195
	s_waitcnt lgkmcnt(1)
	v_add_f32_e32 v193, v142, v143
	v_add_f32_e32 v142, v188, v189
	v_add_f32_e32 v143, v190, v191
	v_add_f32_e32 v142, v142, v143
	ds_bpermute_b32 v143, v167, v142
	ds_bpermute_b32 v194, v168, v193
	s_waitcnt lgkmcnt(1)
	v_add_f32_e32 v191, v142, v143
	v_add_f32_e32 v142, v226, v227
	v_add_f32_e32 v143, v228, v229
	v_add_f32_e32 v142, v142, v143
	ds_bpermute_b32 v143, v167, v142
	ds_bpermute_b32 v192, v168, v191
	s_waitcnt lgkmcnt(1)
	v_add_f32_e32 v189, v142, v143
	v_add_f32_e32 v142, v206, v207
	v_add_f32_e32 v143, v208, v209
	v_add_f32_e32 v142, v142, v143
	ds_bpermute_b32 v143, v167, v142
	ds_bpermute_b32 v190, v168, v189
	s_waitcnt lgkmcnt(1)
	v_add_f32_e32 v187, v142, v143
	v_add_f32_e32 v142, v202, v203
	v_add_f32_e32 v143, v204, v205
	v_add_f32_e32 v142, v142, v143
	ds_bpermute_b32 v143, v167, v142
	ds_bpermute_b32 v188, v168, v187
	s_waitcnt lgkmcnt(1)
	v_add_f32_e32 v185, v142, v143
	v_add_f32_e32 v142, v198, v199
	v_add_f32_e32 v143, v200, v201
	v_add_f32_e32 v142, v142, v143
	ds_bpermute_b32 v143, v167, v142
	ds_bpermute_b32 v186, v168, v185
	v_ashrrev_i32_e32 v198, 12, v160
	s_waitcnt lgkmcnt(1)
	v_add_f32_e32 v169, v142, v143
	ds_bpermute_b32 v184, v168, v169
	s_waitcnt lgkmcnt(0)
	v_mov_b32_e32 v226, v253
	v_add_f32_e32 v227, v195, v196
	v_add_f32_e32 v228, v193, v194
	v_add_f32_e32 v229, v191, v192
	v_add_f32_e32 v230, v189, v190
	v_add_f32_e32 v231, v187, v188
	v_add_f32_e32 v232, v185, v186
	v_add_f32_e32 v233, v169, v184
	v_lshlrev_b32_e32 v254, 5, v212
	v_add_u32_e32 v254, 0x20800, v254
	ds_write_b128 v254, v[226:229]
	ds_write_b128 v254, v[230:233] offset:16
	s_mov_b32 s98, 1
	s_branch .Lssq_join
.Lssq_cached:
	v_and_b32_e32 v143, 64, v216
	v_xor_b32_e32 v142, 16, v216
	v_add_u32_e32 v143, 64, v143
	v_cmp_lt_i32_e32 vcc, v142, v143
	s_cmp_gt_i32 s66, 3
	s_cselect_b64 s[20:21], -1, 0
	v_cndmask_b32_e32 v142, v216, v142, vcc
	v_lshlrev_b32_e32 v167, 2, v142
	v_xor_b32_e32 v142, 32, v216
	v_cmp_lt_i32_e32 vcc, v142, v143
	s_and_b32 s9, s66, 0x7ffffffe
	s_cmp_lg_u32 s9, 4
	v_cndmask_b32_e32 v142, v216, v142, vcc
	v_lshlrev_b32_e32 v168, 2, v142
	s_cselect_b64 s[18:19], -1, 0
	s_cmp_eq_u32 s66, 12
	s_cselect_b64 s[40:41], -1, 0
	s_cmp_lg_u32 s66, 12
	s_cselect_b64 s[22:23], -1, 0
	s_and_b64 s[22:23], s[22:23], s[18:19]
	s_cmp_lg_u32 s9, 6
	s_cselect_b64 s[18:19], -1, 0
	s_lshl_b32 s42, s66, 2
	s_lshl_b32 s67, s66, 8
	s_add_i32 s11, s42, s63
	s_cmp_lt_i32 s66, 2
	s_cselect_b64 s[38:39], -1, 0
	s_and_b64 s[24:25], s[38:39], exec
	s_mov_b32 s9, 0x4548000
	s_cselect_b32 s9, s9, 0x5548000
	v_and_b32_e32 v197, 0xfff, v160
	s_mov_b64 s[24:25], -1
	s_and_b64 vcc, exec, s[20:21]
	v_lshlrev_b32_e32 v254, 5, v212
	v_add_u32_e32 v254, 0x20800, v254
	ds_read_b128 v[226:229], v254
	ds_read_b128 v[230:233], v254 offset:16
	v_ashrrev_i32_e32 v198, 12, v160
	s_waitcnt lgkmcnt(0)
	v_mov_b32_e32 v142, v226
	s_nop 0
	v_fmamk_f32 v142, v142, 0x3a800000, v214
	v_rsq_f32_e32 v158, v142
	v_mov_b32_e32 v195, v227
	v_mov_b32_e32 v196, 0
	v_mov_b32_e32 v193, v228
	v_mov_b32_e32 v194, 0
	v_mov_b32_e32 v191, v229
	v_mov_b32_e32 v192, 0
	v_mov_b32_e32 v189, v230
	v_mov_b32_e32 v190, 0
	v_mov_b32_e32 v187, v231
	v_mov_b32_e32 v188, 0
	v_mov_b32_e32 v185, v232
	v_mov_b32_e32 v186, 0
	v_mov_b32_e32 v169, v233
	v_mov_b32_e32 v184, 0
.Lssq_join:
	v_lshlrev_b32_e32 v142, 3, v0
	v_ashrrev_i32_e32 v143, 31, v142
	s_cbranch_vccz .LBB0_527
	s_and_b64 vcc, exec, s[22:23]
	s_cbranch_vccz .LBB0_524
	s_and_b64 vcc, exec, s[18:19]
	s_cbranch_vccz .LBB0_521
	s_cmp_lt_i32 s66, 10
	s_cbranch_scc1 .LBB0_514
	s_cmp_lt_i32 s66, 11
	s_cbranch_scc1 .LBB0_511
	s_cmp_lg_u32 s66, 11
	s_cbranch_scc0 .LBB0_508
	v_lshlrev_b64 v[162:163], 11, v[160:161]
	v_lshl_add_u64 v[162:163], s[70:71], 0, v[162:163]
	s_lshl_b32 s34, s62, 1
	v_lshl_add_u64 v[162:163], v[162:163], 0, s[34:35]
	s_mov_b64 s[24:25], 0x95c8600
	v_lshl_add_u64 v[162:163], v[162:163], 0, s[24:25]
	s_mov_b64 s[24:25], 0

	.amdhsa_kernel _Z4mega6Paramsii
		.amdhsa_group_segment_fixed_size 16384
		.amdhsa_private_segment_fixed_size 0
		.amdhsa_kernarg_size 360
		.amdhsa_user_sgpr_count 2
		.amdhsa_user_sgpr_dispatch_ptr 0
		.amdhsa_user_sgpr_queue_ptr 0
		.amdhsa_user_sgpr_kernarg_segment_ptr 1
		.amdhsa_user_sgpr_dispatch_id 0
		.amdhsa_user_sgpr_kernarg_preload_length 0
		.amdhsa_user_sgpr_kernarg_preload_offset 0
		.amdhsa_user_sgpr_private_segment_size 0
		.amdhsa_uses_dynamic_stack 0
		.amdhsa_enable_private_segment 0
		.amdhsa_system_sgpr_workgroup_id_x 1
		.amdhsa_system_sgpr_workgroup_id_y 0
		.amdhsa_system_sgpr_workgroup_id_z 0
		.amdhsa_system_sgpr_workgroup_info 0
		.amdhsa_system_vgpr_workitem_id 2
		.amdhsa_next_free_vgpr 256
		.amdhsa_next_free_sgpr 102
		.amdhsa_accum_offset 256
		.amdhsa_reserve_vcc 1
		.amdhsa_float_round_mode_32 0
		.amdhsa_float_round_mode_16_64 0
		.amdhsa_float_denorm_mode_32 3
		.amdhsa_float_denorm_mode_16_64 3
		.amdhsa_dx10_clamp 1
		.amdhsa_ieee_mode 1
		.amdhsa_fp16_overflow 0
		.amdhsa_tg_split 0
		.amdhsa_exception_fp_ieee_invalid_op 0
		.amdhsa_exception_fp_denorm_src 0
		.amdhsa_exception_fp_ieee_div_zero 0
		.amdhsa_exception_fp_ieee_overflow 0
		.amdhsa_exception_fp_ieee_underflow 0
		.amdhsa_exception_fp_ieee_inexact 0
		.amdhsa_exception_int_div_zero 0
	.end_amdhsa_kernel

amdhsa.kernels:
  - .agpr_count:     0
    .args:
      - .offset:         0
        .size:           96
        .value_kind:     by_value
      - .offset:         96
        .size:           4
        .value_kind:     by_value
      - .offset:         100
        .size:           4
        .value_kind:     by_value
      - .offset:         104
        .size:           4
        .value_kind:     hidden_block_count_x
      - .offset:         108
        .size:           4
        .value_kind:     hidden_block_count_y
      - .offset:         112
        .size:           4
        .value_kind:     hidden_block_count_z
      - .offset:         116
        .size:           2
        .value_kind:     hidden_group_size_x
      - .offset:         118
        .size:           2
        .value_kind:     hidden_group_size_y
      - .offset:         120
        .size:           2
        .value_kind:     hidden_group_size_z
      - .offset:         122
        .size:           2
        .value_kind:     hidden_remainder_x
      - .offset:         124
        .size:           2
        .value_kind:     hidden_remainder_y
      - .offset:         126
        .size:           2
        .value_kind:     hidden_remainder_z
      - .offset:         144
        .size:           8
        .value_kind:     hidden_global_offset_x
      - .offset:         152
        .size:           8
        .value_kind:     hidden_global_offset_y
      - .offset:         160
        .size:           8
        .value_kind:     hidden_global_offset_z
      - .offset:         168
        .size:           2
        .value_kind:     hidden_grid_dims
      - .offset:         192
        .size:           8
        .value_kind:     hidden_multigrid_sync_arg
      - .offset:         224
        .size:           4
        .value_kind:     hidden_dynamic_lds_size
    .group_segment_fixed_size: 16384
    .kernarg_segment_align: 8
    .kernarg_segment_size: 360
    .language:       OpenCL C
    .language_version:
      - 2
      - 0
    .max_flat_workgroup_size: 512
    .name:           _Z4mega6Paramsii
    .private_segment_fixed_size: 0
    .sgpr_count:     108
    .sgpr_spill_count: 171
    .symbol:         _Z4mega6Paramsii.kd
    .uniform_work_group_size: 1
    .uses_dynamic_stack: false
    .vgpr_count:     256
    .vgpr_spill_count: 0
    .wavefront_size: 64
